# hand-written post-norm/residual row loop: all loads of two rows issued up front, gains hoisted; plus coalesced foxsum loads
# speedup vs baseline: 1.3856x; 1.3856x over previous
.LBB0_129:
	v_mul_u32_u24_sdwa v0, v42, s16 dst_sel:DWORD dst_unused:UNUSED_PAD src0_sel:WORD_0 src1_sel:DWORD
	v_readlane_b32 s2, v245, 10
	v_readlane_b32 s3, v245, 11
	v_lshrrev_b32_e32 v1, 19, v0
	v_mul_lo_u16_e32 v1, 0x82, v1
	v_sub_u16_e32 v1, v42, v1
	v_lshlrev_b16_e32 v1, 6, v1
	v_lshrrev_b32_e32 v2, 22, v0
	v_mul_u32_u24_e32 v2, 0x2080, v2
	v_bfe_u32 v0, v0, 19, 3
	v_lshrrev_b32_e32 v8, 3, v176
	v_add3_u32 v8, v2, v1, v8
	v_or_b32_e32 v1, v176, v1
	v_add_u32_e32 v4, v2, v1
	v_mul_u32_u24_e32 v4, 0x1618, v4
	v_or_b32_e32 v4, v4, v0
	v_mov_b32_e32 v5, v179
	v_lshl_add_u64 v[4:5], v[4:5], 1, s[56:57]
	global_load_ushort v6, v[4:5], off offset:3072
	v_or_b32_e32 v4, s6, v0
	v_mov_b32_e32 v5, v179
	v_lshl_add_u64 v[4:5], v[4:5], 2, s[2:3]
	global_load_dword v7, v[4:5], off
	v_mul_u32_u24_e32 v8, 0x1618, v8
	v_mov_b32_e32 v9, v179
	v_lshl_add_u64 v[8:9], v[8:9], 1, s[56:57]
	v_lshlrev_b32_e32 v10, 7, v0
	v_and_b32_e32 v11, 7, v176
	v_lshl_add_u32 v10, v11, 4, v10
	v_mov_b32_e32 v11, v179
	v_lshl_add_u64 v[8:9], v[8:9], 0, v[10:11]
	s_mov_b32 s10, 0x16180
	s_mov_b32 s11, 0
	global_load_dwordx4 v[50:53], v[8:9], off
	global_load_dwordx4 v[82:85], v[8:9], off offset:1024
	v_lshl_add_u64 v[8:9], v[8:9], 0, s[10:11]
	global_load_dwordx4 v[54:57], v[8:9], off
	global_load_dwordx4 v[86:89], v[8:9], off offset:1024
	v_lshl_add_u64 v[8:9], v[8:9], 0, s[10:11]
	global_load_dwordx4 v[58:61], v[8:9], off
	global_load_dwordx4 v[90:93], v[8:9], off offset:1024
	v_lshl_add_u64 v[8:9], v[8:9], 0, s[10:11]
	global_load_dwordx4 v[62:65], v[8:9], off
	global_load_dwordx4 v[94:97], v[8:9], off offset:1024
	v_lshl_add_u64 v[8:9], v[8:9], 0, s[10:11]
	global_load_dwordx4 v[66:69], v[8:9], off
	global_load_dwordx4 v[98:101], v[8:9], off offset:1024
	v_lshl_add_u64 v[8:9], v[8:9], 0, s[10:11]
	global_load_dwordx4 v[70:73], v[8:9], off
	global_load_dwordx4 v[102:105], v[8:9], off offset:1024
	v_lshl_add_u64 v[8:9], v[8:9], 0, s[10:11]
	global_load_dwordx4 v[74:77], v[8:9], off
	global_load_dwordx4 v[106:109], v[8:9], off offset:1024
	v_lshl_add_u64 v[8:9], v[8:9], 0, s[10:11]
	global_load_dwordx4 v[78:81], v[8:9], off
	global_load_dwordx4 v[110:113], v[8:9], off offset:1024
	s_waitcnt vmcnt(16)
	v_lshlrev_b32_e32 v6, 16, v6
	v_add_f32_e32 v6, v7, v6
	v_mul_f32_e64 v2, |v6|, s98
	v_exp_f32_e32 v2, v2
	v_min_f32_e32 v3, 0, v6
	v_add_f32_e32 v2, 1.0, v2
	v_log_f32_e32 v2, v2
	v_cmp_gt_u32_e32 vcc, s36, v1
	v_fmac_f32_e32 v3, 0xbf317218, v2
	s_nop 0
	v_cndmask_b32_e64 v3, v3, 0, vcc
	ds_bpermute_b32 v1, v36, v3
	s_waitcnt lgkmcnt(0)
	v_add_f32_e32 v1, v3, v1
	ds_bpermute_b32 v2, v37, v1
	s_waitcnt lgkmcnt(0)
	v_add_f32_e32 v1, v1, v2
	ds_bpermute_b32 v2, v38, v1
	s_waitcnt lgkmcnt(0)
	v_add_f32_e32 v1, v1, v2
	ds_bpermute_b32 v2, v39, v1
	s_waitcnt lgkmcnt(0)
	v_add_f32_e32 v1, v1, v2
	ds_bpermute_b32 v2, v40, v1
	s_waitcnt lgkmcnt(0)
	v_add_f32_e32 v43, v1, v2
	ds_bpermute_b32 v44, v41, v43
	v_mov_b32_e32 v30, 0xffff0000
	s_waitcnt vmcnt(14)
	v_lshlrev_b32_e32 v28, 16, v50
	v_and_b32_e32 v50, v30, v50
	v_mul_f32_e32 v12, v28, v28
	v_fmac_f32_e32 v12, v50, v50
	v_lshlrev_b32_e32 v28, 16, v51
	v_and_b32_e32 v51, v30, v51
	v_fmac_f32_e32 v12, v28, v28
	v_fmac_f32_e32 v12, v51, v51
	v_lshlrev_b32_e32 v28, 16, v52
	v_and_b32_e32 v52, v30, v52
	v_fmac_f32_e32 v12, v28, v28
	v_fmac_f32_e32 v12, v52, v52
	v_lshlrev_b32_e32 v28, 16, v53
	v_and_b32_e32 v53, v30, v53
	v_fmac_f32_e32 v12, v28, v28
	v_fmac_f32_e32 v12, v53, v53
	v_lshlrev_b32_e32 v28, 16, v82
	v_and_b32_e32 v82, v30, v82
	v_mul_f32_e32 v20, v28, v28
	v_fmac_f32_e32 v20, v82, v82
	v_lshlrev_b32_e32 v28, 16, v83
	v_and_b32_e32 v83, v30, v83
	v_fmac_f32_e32 v20, v28, v28
	v_fmac_f32_e32 v20, v83, v83
	v_lshlrev_b32_e32 v28, 16, v84
	v_and_b32_e32 v84, v30, v84
	v_fmac_f32_e32 v20, v28, v28
	v_fmac_f32_e32 v20, v84, v84
	v_lshlrev_b32_e32 v28, 16, v85
	v_and_b32_e32 v85, v30, v85
	v_fmac_f32_e32 v20, v28, v28
	v_fmac_f32_e32 v20, v85, v85
	s_waitcnt vmcnt(12)
	v_lshlrev_b32_e32 v28, 16, v54
	v_and_b32_e32 v54, v30, v54
	v_mul_f32_e32 v13, v28, v28
	v_fmac_f32_e32 v13, v54, v54
	v_lshlrev_b32_e32 v28, 16, v55
	v_and_b32_e32 v55, v30, v55
	v_fmac_f32_e32 v13, v28, v28
	v_fmac_f32_e32 v13, v55, v55
	v_lshlrev_b32_e32 v28, 16, v56
	v_and_b32_e32 v56, v30, v56
	v_fmac_f32_e32 v13, v28, v28
	v_fmac_f32_e32 v13, v56, v56
	v_lshlrev_b32_e32 v28, 16, v57
	v_and_b32_e32 v57, v30, v57
	v_fmac_f32_e32 v13, v28, v28
	v_fmac_f32_e32 v13, v57, v57
	v_lshlrev_b32_e32 v28, 16, v86
	v_and_b32_e32 v86, v30, v86
	v_mul_f32_e32 v21, v28, v28
	v_fmac_f32_e32 v21, v86, v86
	v_lshlrev_b32_e32 v28, 16, v87
	v_and_b32_e32 v87, v30, v87
	v_fmac_f32_e32 v21, v28, v28
	v_fmac_f32_e32 v21, v87, v87
	v_lshlrev_b32_e32 v28, 16, v88
	v_and_b32_e32 v88, v30, v88
	v_fmac_f32_e32 v21, v28, v28
	v_fmac_f32_e32 v21, v88, v88
	v_lshlrev_b32_e32 v28, 16, v89
	v_and_b32_e32 v89, v30, v89
	v_fmac_f32_e32 v21, v28, v28
	v_fmac_f32_e32 v21, v89, v89
	s_waitcnt vmcnt(10)
	v_lshlrev_b32_e32 v28, 16, v58
	v_and_b32_e32 v58, v30, v58
	v_mul_f32_e32 v14, v28, v28
	v_fmac_f32_e32 v14, v58, v58
	v_lshlrev_b32_e32 v28, 16, v59
	v_and_b32_e32 v59, v30, v59
	v_fmac_f32_e32 v14, v28, v28
	v_fmac_f32_e32 v14, v59, v59
	v_lshlrev_b32_e32 v28, 16, v60
	v_and_b32_e32 v60, v30, v60
	v_fmac_f32_e32 v14, v28, v28
	v_fmac_f32_e32 v14, v60, v60
	v_lshlrev_b32_e32 v28, 16, v61
	v_and_b32_e32 v61, v30, v61
	v_fmac_f32_e32 v14, v28, v28
	v_fmac_f32_e32 v14, v61, v61
	v_lshlrev_b32_e32 v28, 16, v90
	v_and_b32_e32 v90, v30, v90
	v_mul_f32_e32 v22, v28, v28
	v_fmac_f32_e32 v22, v90, v90
	v_lshlrev_b32_e32 v28, 16, v91
	v_and_b32_e32 v91, v30, v91
	v_fmac_f32_e32 v22, v28, v28
	v_fmac_f32_e32 v22, v91, v91
	v_lshlrev_b32_e32 v28, 16, v92
	v_and_b32_e32 v92, v30, v92
	v_fmac_f32_e32 v22, v28, v28
	v_fmac_f32_e32 v22, v92, v92
	v_lshlrev_b32_e32 v28, 16, v93
	v_and_b32_e32 v93, v30, v93
	v_fmac_f32_e32 v22, v28, v28
	v_fmac_f32_e32 v22, v93, v93
	s_waitcnt vmcnt(8)
	v_lshlrev_b32_e32 v28, 16, v62
	v_and_b32_e32 v62, v30, v62
	v_mul_f32_e32 v15, v28, v28
	v_fmac_f32_e32 v15, v62, v62
	v_lshlrev_b32_e32 v28, 16, v63
	v_and_b32_e32 v63, v30, v63
	v_fmac_f32_e32 v15, v28, v28
	v_fmac_f32_e32 v15, v63, v63
	v_lshlrev_b32_e32 v28, 16, v64
	v_and_b32_e32 v64, v30, v64
	v_fmac_f32_e32 v15, v28, v28
	v_fmac_f32_e32 v15, v64, v64
	v_lshlrev_b32_e32 v28, 16, v65
	v_and_b32_e32 v65, v30, v65
	v_fmac_f32_e32 v15, v28, v28
	v_fmac_f32_e32 v15, v65, v65
	v_lshlrev_b32_e32 v28, 16, v94
	v_and_b32_e32 v94, v30, v94
	v_mul_f32_e32 v23, v28, v28
	v_fmac_f32_e32 v23, v94, v94
	v_lshlrev_b32_e32 v28, 16, v95
	v_and_b32_e32 v95, v30, v95
	v_fmac_f32_e32 v23, v28, v28
	v_fmac_f32_e32 v23, v95, v95
	v_lshlrev_b32_e32 v28, 16, v96
	v_and_b32_e32 v96, v30, v96
	v_fmac_f32_e32 v23, v28, v28
	v_fmac_f32_e32 v23, v96, v96
	v_lshlrev_b32_e32 v28, 16, v97
	v_and_b32_e32 v97, v30, v97
	v_fmac_f32_e32 v23, v28, v28
	v_fmac_f32_e32 v23, v97, v97
	s_waitcnt vmcnt(6)
	v_lshlrev_b32_e32 v28, 16, v66
	v_and_b32_e32 v66, v30, v66
	v_mul_f32_e32 v16, v28, v28
	v_fmac_f32_e32 v16, v66, v66
	v_lshlrev_b32_e32 v28, 16, v67
	v_and_b32_e32 v67, v30, v67
	v_fmac_f32_e32 v16, v28, v28
	v_fmac_f32_e32 v16, v67, v67
	v_lshlrev_b32_e32 v28, 16, v68
	v_and_b32_e32 v68, v30, v68
	v_fmac_f32_e32 v16, v28, v28
	v_fmac_f32_e32 v16, v68, v68
	v_lshlrev_b32_e32 v28, 16, v69
	v_and_b32_e32 v69, v30, v69
	v_fmac_f32_e32 v16, v28, v28
	v_fmac_f32_e32 v16, v69, v69
	v_lshlrev_b32_e32 v28, 16, v98
	v_and_b32_e32 v98, v30, v98
	v_mul_f32_e32 v24, v28, v28
	v_fmac_f32_e32 v24, v98, v98
	v_lshlrev_b32_e32 v28, 16, v99
	v_and_b32_e32 v99, v30, v99
	v_fmac_f32_e32 v24, v28, v28
	v_fmac_f32_e32 v24, v99, v99
	v_lshlrev_b32_e32 v28, 16, v100
	v_and_b32_e32 v100, v30, v100
	v_fmac_f32_e32 v24, v28, v28
	v_fmac_f32_e32 v24, v100, v100
	v_lshlrev_b32_e32 v28, 16, v101
	v_and_b32_e32 v101, v30, v101
	v_fmac_f32_e32 v24, v28, v28
	v_fmac_f32_e32 v24, v101, v101
	s_waitcnt vmcnt(4)
	v_lshlrev_b32_e32 v28, 16, v70
	v_and_b32_e32 v70, v30, v70
	v_mul_f32_e32 v17, v28, v28
	v_fmac_f32_e32 v17, v70, v70
	v_lshlrev_b32_e32 v28, 16, v71
	v_and_b32_e32 v71, v30, v71
	v_fmac_f32_e32 v17, v28, v28
	v_fmac_f32_e32 v17, v71, v71
	v_lshlrev_b32_e32 v28, 16, v72
	v_and_b32_e32 v72, v30, v72
	v_fmac_f32_e32 v17, v28, v28
	v_fmac_f32_e32 v17, v72, v72
	v_lshlrev_b32_e32 v28, 16, v73
	v_and_b32_e32 v73, v30, v73
	v_fmac_f32_e32 v17, v28, v28
	v_fmac_f32_e32 v17, v73, v73
	v_lshlrev_b32_e32 v28, 16, v102
	v_and_b32_e32 v102, v30, v102
	v_mul_f32_e32 v25, v28, v28
	v_fmac_f32_e32 v25, v102, v102
	v_lshlrev_b32_e32 v28, 16, v103
	v_and_b32_e32 v103, v30, v103
	v_fmac_f32_e32 v25, v28, v28
	v_fmac_f32_e32 v25, v103, v103
	v_lshlrev_b32_e32 v28, 16, v104
	v_and_b32_e32 v104, v30, v104
	v_fmac_f32_e32 v25, v28, v28
	v_fmac_f32_e32 v25, v104, v104
	v_lshlrev_b32_e32 v28, 16, v105
	v_and_b32_e32 v105, v30, v105
	v_fmac_f32_e32 v25, v28, v28
	v_fmac_f32_e32 v25, v105, v105
	s_waitcnt vmcnt(2)
	v_lshlrev_b32_e32 v28, 16, v74
	v_and_b32_e32 v74, v30, v74
	v_mul_f32_e32 v18, v28, v28
	v_fmac_f32_e32 v18, v74, v74
	v_lshlrev_b32_e32 v28, 16, v75
	v_and_b32_e32 v75, v30, v75
	v_fmac_f32_e32 v18, v28, v28
	v_fmac_f32_e32 v18, v75, v75
	v_lshlrev_b32_e32 v28, 16, v76
	v_and_b32_e32 v76, v30, v76
	v_fmac_f32_e32 v18, v28, v28
	v_fmac_f32_e32 v18, v76, v76
	v_lshlrev_b32_e32 v28, 16, v77
	v_and_b32_e32 v77, v30, v77
	v_fmac_f32_e32 v18, v28, v28
	v_fmac_f32_e32 v18, v77, v77
	v_lshlrev_b32_e32 v28, 16, v106
	v_and_b32_e32 v106, v30, v106
	v_mul_f32_e32 v26, v28, v28
	v_fmac_f32_e32 v26, v106, v106
	v_lshlrev_b32_e32 v28, 16, v107
	v_and_b32_e32 v107, v30, v107
	v_fmac_f32_e32 v26, v28, v28
	v_fmac_f32_e32 v26, v107, v107
	v_lshlrev_b32_e32 v28, 16, v108
	v_and_b32_e32 v108, v30, v108
	v_fmac_f32_e32 v26, v28, v28
	v_fmac_f32_e32 v26, v108, v108
	v_lshlrev_b32_e32 v28, 16, v109
	v_and_b32_e32 v109, v30, v109
	v_fmac_f32_e32 v26, v28, v28
	v_fmac_f32_e32 v26, v109, v109
	s_waitcnt vmcnt(0)
	v_lshlrev_b32_e32 v28, 16, v78
	v_and_b32_e32 v78, v30, v78
	v_mul_f32_e32 v19, v28, v28
	v_fmac_f32_e32 v19, v78, v78
	v_lshlrev_b32_e32 v28, 16, v79
	v_and_b32_e32 v79, v30, v79
	v_fmac_f32_e32 v19, v28, v28
	v_fmac_f32_e32 v19, v79, v79
	v_lshlrev_b32_e32 v28, 16, v80
	v_and_b32_e32 v80, v30, v80
	v_fmac_f32_e32 v19, v28, v28
	v_fmac_f32_e32 v19, v80, v80
	v_lshlrev_b32_e32 v28, 16, v81
	v_and_b32_e32 v81, v30, v81
	v_fmac_f32_e32 v19, v28, v28
	v_fmac_f32_e32 v19, v81, v81
	v_lshlrev_b32_e32 v28, 16, v110
	v_and_b32_e32 v110, v30, v110
	v_mul_f32_e32 v27, v28, v28
	v_fmac_f32_e32 v27, v110, v110
	v_lshlrev_b32_e32 v28, 16, v111
	v_and_b32_e32 v111, v30, v111
	v_fmac_f32_e32 v27, v28, v28
	v_fmac_f32_e32 v27, v111, v111
	v_lshlrev_b32_e32 v28, 16, v112
	v_and_b32_e32 v112, v30, v112
	v_fmac_f32_e32 v27, v28, v28
	v_fmac_f32_e32 v27, v112, v112
	v_lshlrev_b32_e32 v28, 16, v113
	v_and_b32_e32 v113, v30, v113
	v_fmac_f32_e32 v27, v28, v28
	v_fmac_f32_e32 v27, v113, v113
	s_nop 1
	v_add_f32_dpp v12, v12, v12 quad_perm:[1,0,3,2] row_mask:0xf bank_mask:0xf
	v_add_f32_dpp v13, v13, v13 quad_perm:[1,0,3,2] row_mask:0xf bank_mask:0xf
	v_add_f32_dpp v14, v14, v14 quad_perm:[1,0,3,2] row_mask:0xf bank_mask:0xf
	v_add_f32_dpp v15, v15, v15 quad_perm:[1,0,3,2] row_mask:0xf bank_mask:0xf
	v_add_f32_dpp v16, v16, v16 quad_perm:[1,0,3,2] row_mask:0xf bank_mask:0xf
	v_add_f32_dpp v17, v17, v17 quad_perm:[1,0,3,2] row_mask:0xf bank_mask:0xf
	v_add_f32_dpp v18, v18, v18 quad_perm:[1,0,3,2] row_mask:0xf bank_mask:0xf
	v_add_f32_dpp v19, v19, v19 quad_perm:[1,0,3,2] row_mask:0xf bank_mask:0xf
	v_add_f32_dpp v20, v20, v20 quad_perm:[1,0,3,2] row_mask:0xf bank_mask:0xf
	v_add_f32_dpp v21, v21, v21 quad_perm:[1,0,3,2] row_mask:0xf bank_mask:0xf
	v_add_f32_dpp v22, v22, v22 quad_perm:[1,0,3,2] row_mask:0xf bank_mask:0xf
	v_add_f32_dpp v23, v23, v23 quad_perm:[1,0,3,2] row_mask:0xf bank_mask:0xf
	v_add_f32_dpp v24, v24, v24 quad_perm:[1,0,3,2] row_mask:0xf bank_mask:0xf
	v_add_f32_dpp v25, v25, v25 quad_perm:[1,0,3,2] row_mask:0xf bank_mask:0xf
	v_add_f32_dpp v26, v26, v26 quad_perm:[1,0,3,2] row_mask:0xf bank_mask:0xf
	v_add_f32_dpp v27, v27, v27 quad_perm:[1,0,3,2] row_mask:0xf bank_mask:0xf
	s_nop 1
	v_add_f32_dpp v12, v12, v12 quad_perm:[2,3,0,1] row_mask:0xf bank_mask:0xf
	v_add_f32_dpp v13, v13, v13 quad_perm:[2,3,0,1] row_mask:0xf bank_mask:0xf
	v_add_f32_dpp v14, v14, v14 quad_perm:[2,3,0,1] row_mask:0xf bank_mask:0xf
	v_add_f32_dpp v15, v15, v15 quad_perm:[2,3,0,1] row_mask:0xf bank_mask:0xf
	v_add_f32_dpp v16, v16, v16 quad_perm:[2,3,0,1] row_mask:0xf bank_mask:0xf
	v_add_f32_dpp v17, v17, v17 quad_perm:[2,3,0,1] row_mask:0xf bank_mask:0xf
	v_add_f32_dpp v18, v18, v18 quad_perm:[2,3,0,1] row_mask:0xf bank_mask:0xf
	v_add_f32_dpp v19, v19, v19 quad_perm:[2,3,0,1] row_mask:0xf bank_mask:0xf
	v_add_f32_dpp v20, v20, v20 quad_perm:[2,3,0,1] row_mask:0xf bank_mask:0xf
	v_add_f32_dpp v21, v21, v21 quad_perm:[2,3,0,1] row_mask:0xf bank_mask:0xf
	v_add_f32_dpp v22, v22, v22 quad_perm:[2,3,0,1] row_mask:0xf bank_mask:0xf
	v_add_f32_dpp v23, v23, v23 quad_perm:[2,3,0,1] row_mask:0xf bank_mask:0xf
	v_add_f32_dpp v24, v24, v24 quad_perm:[2,3,0,1] row_mask:0xf bank_mask:0xf
	v_add_f32_dpp v25, v25, v25 quad_perm:[2,3,0,1] row_mask:0xf bank_mask:0xf
	v_add_f32_dpp v26, v26, v26 quad_perm:[2,3,0,1] row_mask:0xf bank_mask:0xf
	v_add_f32_dpp v27, v27, v27 quad_perm:[2,3,0,1] row_mask:0xf bank_mask:0xf
	s_nop 1
	v_add_f32_dpp v12, v12, v12 row_half_mirror row_mask:0xf bank_mask:0xf
	v_add_f32_dpp v13, v13, v13 row_half_mirror row_mask:0xf bank_mask:0xf
	v_add_f32_dpp v14, v14, v14 row_half_mirror row_mask:0xf bank_mask:0xf
	v_add_f32_dpp v15, v15, v15 row_half_mirror row_mask:0xf bank_mask:0xf
	v_add_f32_dpp v16, v16, v16 row_half_mirror row_mask:0xf bank_mask:0xf
	v_add_f32_dpp v17, v17, v17 row_half_mirror row_mask:0xf bank_mask:0xf
	v_add_f32_dpp v18, v18, v18 row_half_mirror row_mask:0xf bank_mask:0xf
	v_add_f32_dpp v19, v19, v19 row_half_mirror row_mask:0xf bank_mask:0xf
	v_add_f32_dpp v20, v20, v20 row_half_mirror row_mask:0xf bank_mask:0xf
	v_add_f32_dpp v21, v21, v21 row_half_mirror row_mask:0xf bank_mask:0xf
	v_add_f32_dpp v22, v22, v22 row_half_mirror row_mask:0xf bank_mask:0xf
	v_add_f32_dpp v23, v23, v23 row_half_mirror row_mask:0xf bank_mask:0xf
	v_add_f32_dpp v24, v24, v24 row_half_mirror row_mask:0xf bank_mask:0xf
	v_add_f32_dpp v25, v25, v25 row_half_mirror row_mask:0xf bank_mask:0xf
	v_add_f32_dpp v26, v26, v26 row_half_mirror row_mask:0xf bank_mask:0xf
	v_add_f32_dpp v27, v27, v27 row_half_mirror row_mask:0xf bank_mask:0xf
	s_nop 1
	v_max3_f32 v12, v12, v13, v14
	v_max3_f32 v12, v12, v15, v16
	v_max3_f32 v12, v12, v17, v18
	v_max_f32_e32 v12, v12, v19
	v_max3_f32 v20, v20, v21, v22
	v_max3_f32 v20, v20, v23, v24
	v_max3_f32 v20, v20, v25, v26
	v_max_f32_e32 v20, v20, v27
	s_nop 1
	v_max_f32_dpp v13, v12, v12 row_ror:8 row_mask:0xf bank_mask:0xf
	v_max_f32_dpp v21, v20, v20 row_ror:8 row_mask:0xf bank_mask:0xf
	s_nop 0
	v_max_f32_e32 v12, v12, v13
	v_max_f32_e32 v20, v20, v21
	ds_bpermute_b32 v13, v37, v12
	ds_bpermute_b32 v21, v37, v20
	s_waitcnt lgkmcnt(0)
	v_max_f32_e32 v12, v12, v13
	v_max_f32_e32 v20, v20, v21
	ds_bpermute_b32 v13, v36, v12
	ds_bpermute_b32 v21, v36, v20
	s_waitcnt lgkmcnt(0)
	v_max_f32_e32 v2, v12, v13
	v_max_f32_e32 v3, v20, v21
	v_add_f32_e32 v4, v43, v44
	s_mov_b64 s[2:3], exec
	v_readlane_b32 s10, v245, 63
	v_readlane_b32 s11, v244, 0
	s_and_b64 s[10:11], s[2:3], s[10:11]
	s_mov_b64 exec, s[10:11]
	global_store_dword v[32:33], v4, off
	global_store_dwordx2 v[34:35], v[2:3], off offset:-4
	s_branch .LBB0_128

.LBB0_380:
	s_or_b64 exec, exec, s[0:1]
	s_barrier
	s_mov_b64 s[8:9], exec
	v_readlane_b32 s0, v245, 18
	v_readlane_b32 s1, v245, 19
	s_and_b64 s[0:1], s[8:9], s[0:1]
	s_mov_b64 exec, s[0:1]
	s_cbranch_execz .LBB0_405
	v_readlane_b32 s14, v245, 61
	v_lshlrev_b32_e32 v40, 4, v176
	v_lshrrev_b32_e32 v41, 3, v176
	s_mov_b32 s2, 0x208000
	v_mul_lo_u32 v41, v41, s2
	v_and_b32_e32 v0, 7, v176
	v_lshl_add_u32 v41, v0, 3, v41
	v_xor_b32_e32 v42, 16, v176
	v_lshlrev_b32_e32 v42, 2, v42
	v_xor_b32_e32 v43, 32, v176
	v_lshlrev_b32_e32 v43, 2, v43
	v_mov_b32_e32 v52, 0
	v_mov_b32_e32 v53, 0
	s_lshl_b32 s2, s14, 12
	s_mov_b32 s3, 0
	v_lshl_add_u64 v[16:17], v[190:191], 0, s[2:3]
	global_load_dwordx4 v[60:63], v[16:17], off offset:0
	global_load_dwordx4 v[64:67], v[16:17], off offset:1024
	global_load_dwordx4 v[68:71], v[16:17], off offset:2048
	global_load_dwordx4 v[72:75], v[16:17], off offset:3072
	s_cmp_lg_u32 s14, 0
	s_cbranch_scc1 .Lpost_l1setup
	global_load_dwordx4 v[76:79], v[182:183], off
	global_load_dwordx4 v[80:83], v[184:185], off
	global_load_dwordx4 v[84:87], v[186:187], off
	global_load_dwordx4 v[88:91], v[188:189], off
	v_readlane_b32 s68, v245, 2
	v_readlane_b32 s69, v245, 3
	v_readlane_b32 s70, v245, 4
	v_readlane_b32 s71, v245, 5
	s_mov_b32 s15, 0
	s_movk_i32 s11, 0x70
	s_branch .Lpost_setupdone
.Lpost_l1setup:
	s_mov_b64 s[68:69], s[54:55]
	s_mov_b64 s[70:71], s[62:63]
	s_mov_b32 s15, 16
	s_movk_i32 s11, 0x80
.Lpost_setupdone:
	v_readfirstlane_b32 s0, v214
	s_nop 0
.Lpost_loop:
	s_mov_b32 s2, 0
	s_cmp_ge_u32 s0, 8320
	s_addc_u32 s2, s2, 0
	s_cmp_ge_u32 s0, 16640
	s_addc_u32 s2, s2, 0
	s_cmp_ge_u32 s0, 24960
	s_addc_u32 s2, s2, 0
	s_mulk_i32 s2, 0x2080
	s_sub_u32 s18, s0, s2
	s_lshr_b32 s2, s2, 6
	s_mov_b32 s10, 0
	s_cmp_ge_u32 s0, 8320
	s_addc_u32 s10, s10, 0
	s_cmp_ge_u32 s0, 16640
	s_addc_u32 s10, s10, 0
	s_cmp_ge_u32 s0, 24960
	s_addc_u32 s10, s10, 0
	s_lshl_b32 s6, s0, 6
	s_lshl_b32 s2, s10, 13
	s_add_u32 s2, s2, s18
	s_sub_u32 s2, s2, 0x80
	s_mul_i32 s3, s10, s15
	s_add_u32 s3, s3, s18
	s_sub_u32 s3, s3, 0x70
	s_lshl_b32 s10, s10, 4
	s_add_u32 s10, s10, s18
	s_sub_u32 s10, s10, 0x70
	s_cmp_lt_u32 s18, 0x80
	s_cselect_b32 s74, s70, s68
	s_cselect_b32 s75, s71, s69
	s_cselect_b32 s3, s3, s2
	s_cselect_b32 s76, s62, s54
	s_cselect_b32 s77, s63, s55
	s_cselect_b32 s2, s10, s2
	s_lshl_b32 s3, s3, 12
	s_lshl_b32 s2, s2, 12
	s_add_u32 s74, s74, s3
	s_addc_u32 s75, s75, 0
	s_add_u32 s76, s76, s2
	s_addc_u32 s77, s77, 0
	v_add_u32_e32 v44, s6, v41
	v_add_u32_e32 v45, 0x1040000, v44
	v_add_u32_e32 v46, 0x2080000, v44
	v_add_u32_e32 v47, 0x30c0000, v44
	s_add_u32 s1, s0, s33
	s_mov_b32 s19, 0
	s_mov_b32 s82, 0
	s_cmp_ge_u32 s1, 33280
	s_cbranch_scc1 .Lpost_noB
	s_mov_b32 s82, 1
	s_mov_b32 s2, 0
	s_cmp_ge_u32 s1, 8320
	s_addc_u32 s2, s2, 0
	s_cmp_ge_u32 s1, 16640
	s_addc_u32 s2, s2, 0
	s_cmp_ge_u32 s1, 24960
	s_addc_u32 s2, s2, 0
	s_mulk_i32 s2, 0x2080
	s_sub_u32 s19, s1, s2
	s_lshr_b32 s2, s2, 6
	s_mov_b32 s10, 0
	s_cmp_ge_u32 s1, 8320
	s_addc_u32 s10, s10, 0
	s_cmp_ge_u32 s1, 16640
	s_addc_u32 s10, s10, 0
	s_cmp_ge_u32 s1, 24960
	s_addc_u32 s10, s10, 0
	s_lshl_b32 s7, s1, 6
	s_lshl_b32 s2, s10, 13
	s_add_u32 s2, s2, s19
	s_sub_u32 s2, s2, 0x80
	s_mul_i32 s3, s10, s15
	s_add_u32 s3, s3, s19
	s_sub_u32 s3, s3, 0x70
	s_lshl_b32 s10, s10, 4
	s_add_u32 s10, s10, s19
	s_sub_u32 s10, s10, 0x70
	s_cmp_lt_u32 s19, 0x80
	s_cselect_b32 s78, s70, s68
	s_cselect_b32 s79, s71, s69
	s_cselect_b32 s3, s3, s2
	s_cselect_b32 s80, s62, s54
	s_cselect_b32 s81, s63, s55
	s_cselect_b32 s2, s10, s2
	s_lshl_b32 s3, s3, 12
	s_lshl_b32 s2, s2, 12
	s_add_u32 s78, s78, s3
	s_addc_u32 s79, s79, 0
	s_add_u32 s80, s80, s2
	s_addc_u32 s81, s81, 0
	v_add_u32_e32 v48, s7, v41
	v_add_u32_e32 v49, 0x1040000, v48
	v_add_u32_e32 v50, 0x2080000, v48
	v_add_u32_e32 v51, 0x30c0000, v48
.Lpost_noB:
	s_cmp_ge_u32 s18, s11
	s_cselect_b32 s72, 1, 0
	s_cmp_ge_u32 s19, s11
	s_cselect_b32 s73, 1, 0
	s_and_b32 s73, s73, s82
	s_cmp_eq_u32 s72, 0
	s_cbranch_scc1 .Lpost_noLA
	global_load_dwordx2 v[0:1], v44, s[58:59]
	global_load_dwordx2 v[2:3], v45, s[58:59]
	global_load_dwordx2 v[4:5], v46, s[58:59]
	global_load_dwordx2 v[6:7], v47, s[58:59]
	global_load_dwordx4 v[8:11], v40, s[74:75] offset:0
	global_load_dwordx4 v[12:15], v40, s[74:75] offset:1024
	global_load_dwordx4 v[16:19], v40, s[74:75] offset:2048
	global_load_dwordx4 v[20:23], v40, s[74:75] offset:3072
.Lpost_noLA:
	s_cmp_eq_u32 s73, 0
	s_cbranch_scc1 .Lpost_noLB
	global_load_dwordx2 v[24:25], v48, s[58:59]
	global_load_dwordx2 v[26:27], v49, s[58:59]
	global_load_dwordx2 v[28:29], v50, s[58:59]
	global_load_dwordx2 v[30:31], v51, s[58:59]
	global_load_dwordx4 v[92:95], v40, s[78:79] offset:0
	global_load_dwordx4 v[96:99], v40, s[78:79] offset:1024
	global_load_dwordx4 v[100:103], v40, s[78:79] offset:2048
	global_load_dwordx4 v[104:107], v40, s[78:79] offset:3072
.Lpost_noLB:
	s_cmp_eq_u32 s72, 0
	s_cbranch_scc1 .Lpost_noCA
	s_cmp_eq_u32 s73, 0
	s_cbranch_scc1 .Lpost_wA0
	s_waitcnt vmcnt(8)
	s_branch .Lpost_cA
.Lpost_wA0:
	s_waitcnt vmcnt(0)
.Lpost_cA:
	v_lshlrev_b32_e32 v108, 16, v0
	v_and_b32_e32 v109, 0xffff0000, v0
	v_lshlrev_b32_e32 v110, 16, v1
	v_and_b32_e32 v111, 0xffff0000, v1
	v_lshlrev_b32_e32 v112, 16, v2
	v_and_b32_e32 v113, 0xffff0000, v2
	v_lshlrev_b32_e32 v114, 16, v3
	v_and_b32_e32 v115, 0xffff0000, v3
	v_lshlrev_b32_e32 v116, 16, v4
	v_and_b32_e32 v117, 0xffff0000, v4
	v_lshlrev_b32_e32 v118, 16, v5
	v_and_b32_e32 v119, 0xffff0000, v5
	v_lshlrev_b32_e32 v120, 16, v6
	v_and_b32_e32 v121, 0xffff0000, v6
	v_lshlrev_b32_e32 v122, 16, v7
	v_and_b32_e32 v123, 0xffff0000, v7
	v_mul_f32_e32 v56, v108, v108
	v_mul_f32_e32 v57, v109, v109
	v_fmac_f32_e32 v56, v110, v110
	v_fmac_f32_e32 v57, v111, v111
	v_fmac_f32_e32 v56, v112, v112
	v_fmac_f32_e32 v57, v113, v113
	v_fmac_f32_e32 v56, v114, v114
	v_fmac_f32_e32 v57, v115, v115
	v_fmac_f32_e32 v56, v116, v116
	v_fmac_f32_e32 v57, v117, v117
	v_fmac_f32_e32 v56, v118, v118
	v_fmac_f32_e32 v57, v119, v119
	v_fmac_f32_e32 v56, v120, v120
	v_fmac_f32_e32 v57, v121, v121
	v_fmac_f32_e32 v56, v122, v122
	v_fmac_f32_e32 v57, v123, v123
	v_add_f32_e32 v56, v56, v57
	s_nop 1
	v_add_f32_dpp v56, v56, v56 quad_perm:[1,0,3,2] row_mask:0xf bank_mask:0xf
	s_nop 1
	v_add_f32_dpp v56, v56, v56 quad_perm:[2,3,0,1] row_mask:0xf bank_mask:0xf
	s_nop 1
	v_add_f32_dpp v56, v56, v56 row_half_mirror row_mask:0xf bank_mask:0xf
	s_nop 1
	v_add_f32_dpp v56, v56, v56 row_ror:8 row_mask:0xf bank_mask:0xf
	ds_bpermute_b32 v57, v42, v56
	s_waitcnt lgkmcnt(0)
	v_add_f32_e32 v56, v56, v57
	ds_bpermute_b32 v57, v43, v56
	s_waitcnt lgkmcnt(0)
	v_add_f32_e32 v56, v56, v57
	v_fmamk_f32 v56, v56, 0x3a800000, v221
	v_rsq_f32_e32 v56, v56
	s_nop 0
	v_mul_f32_e32 v108, v56, v108
	v_fma_f32 v8, v108, v60, v8
	v_mul_f32_e32 v109, v56, v109
	v_fma_f32 v9, v109, v61, v9
	v_mul_f32_e32 v110, v56, v110
	v_fma_f32 v10, v110, v62, v10
	v_mul_f32_e32 v111, v56, v111
	v_fma_f32 v11, v111, v63, v11
	v_mul_f32_e32 v112, v56, v112
	v_fma_f32 v12, v112, v64, v12
	v_mul_f32_e32 v113, v56, v113
	v_fma_f32 v13, v113, v65, v13
	v_mul_f32_e32 v114, v56, v114
	v_fma_f32 v14, v114, v66, v14
	v_mul_f32_e32 v115, v56, v115
	v_fma_f32 v15, v115, v67, v15
	v_mul_f32_e32 v116, v56, v116
	v_fma_f32 v16, v116, v68, v16
	v_mul_f32_e32 v117, v56, v117
	v_fma_f32 v17, v117, v69, v17
	v_mul_f32_e32 v118, v56, v118
	v_fma_f32 v18, v118, v70, v18
	v_mul_f32_e32 v119, v56, v119
	v_fma_f32 v19, v119, v71, v19
	v_mul_f32_e32 v120, v56, v120
	v_fma_f32 v20, v120, v72, v20
	v_mul_f32_e32 v121, v56, v121
	v_fma_f32 v21, v121, v73, v21
	v_mul_f32_e32 v122, v56, v122
	v_fma_f32 v22, v122, v74, v22
	v_mul_f32_e32 v123, v56, v123
	v_fma_f32 v23, v123, v75, v23
	s_cmp_lg_u32 s14, 0
	s_cbranch_scc1 .Lpost_cA_done
	v_mul_f32_e32 v56, v8, v8
	v_mul_f32_e32 v57, v9, v9
	v_fmac_f32_e32 v56, v10, v10
	v_fmac_f32_e32 v57, v11, v11
	v_fmac_f32_e32 v56, v12, v12
	v_fmac_f32_e32 v57, v13, v13
	v_fmac_f32_e32 v56, v14, v14
	v_fmac_f32_e32 v57, v15, v15
	v_fmac_f32_e32 v56, v16, v16
	v_fmac_f32_e32 v57, v17, v17
	v_fmac_f32_e32 v56, v18, v18
	v_fmac_f32_e32 v57, v19, v19
	v_fmac_f32_e32 v56, v20, v20
	v_fmac_f32_e32 v57, v21, v21
	v_fmac_f32_e32 v56, v22, v22
	v_fmac_f32_e32 v57, v23, v23
	v_add_f32_e32 v56, v56, v57
	s_nop 1
	v_add_f32_dpp v56, v56, v56 quad_perm:[1,0,3,2] row_mask:0xf bank_mask:0xf
	s_nop 1
	v_add_f32_dpp v56, v56, v56 quad_perm:[2,3,0,1] row_mask:0xf bank_mask:0xf
	s_nop 1
	v_add_f32_dpp v56, v56, v56 row_half_mirror row_mask:0xf bank_mask:0xf
	s_nop 1
	v_add_f32_dpp v56, v56, v56 row_ror:8 row_mask:0xf bank_mask:0xf
	ds_bpermute_b32 v57, v42, v56
	s_waitcnt lgkmcnt(0)
	v_add_f32_e32 v56, v56, v57
	ds_bpermute_b32 v57, v43, v56
	s_waitcnt lgkmcnt(0)
	v_add_f32_e32 v56, v56, v57
	v_fmamk_f32 v56, v56, 0x3a800000, v221
	v_rsq_f32_e32 v56, v56
	s_nop 0
	v_mul_f32_e32 v108, v8, v56
	v_mul_f32_e32 v108, v76, v108
	v_mul_f32_e32 v109, v9, v56
	v_mul_f32_e32 v109, v77, v109
	v_mul_f32_e32 v110, v10, v56
	v_mul_f32_e32 v110, v78, v110
	v_mul_f32_e32 v111, v11, v56
	v_mul_f32_e32 v111, v79, v111
	v_mul_f32_e32 v112, v12, v56
	v_mul_f32_e32 v112, v80, v112
	v_mul_f32_e32 v113, v13, v56
	v_mul_f32_e32 v113, v81, v113
	v_mul_f32_e32 v114, v14, v56
	v_mul_f32_e32 v114, v82, v114
	v_mul_f32_e32 v115, v15, v56
	v_mul_f32_e32 v115, v83, v115
	v_mul_f32_e32 v116, v16, v56
	v_mul_f32_e32 v116, v84, v116
	v_mul_f32_e32 v117, v17, v56
	v_mul_f32_e32 v117, v85, v117
	v_mul_f32_e32 v118, v18, v56
	v_mul_f32_e32 v118, v86, v118
	v_mul_f32_e32 v119, v19, v56
	v_mul_f32_e32 v119, v87, v119
	v_mul_f32_e32 v120, v20, v56
	v_mul_f32_e32 v120, v88, v120
	v_mul_f32_e32 v121, v21, v56
	v_mul_f32_e32 v121, v89, v121
	v_mul_f32_e32 v122, v22, v56
	v_mul_f32_e32 v122, v90, v122
	v_mul_f32_e32 v123, v23, v56
	v_mul_f32_e32 v123, v91, v123
	v_cvt_pk_bf16_f32 v0, v108, v109
	v_cvt_pk_bf16_f32 v1, v110, v111
	v_cvt_pk_bf16_f32 v2, v112, v113
	v_cvt_pk_bf16_f32 v3, v114, v115
	v_cvt_pk_bf16_f32 v4, v116, v117
	v_cvt_pk_bf16_f32 v5, v118, v119
	v_cvt_pk_bf16_f32 v6, v120, v121
	v_cvt_pk_bf16_f32 v7, v122, v123
.Lpost_cA_done:
.Lpost_noCA:
	s_cmp_eq_u32 s73, 0
	s_cbranch_scc1 .Lpost_noCB
	s_waitcnt vmcnt(0)
	v_lshlrev_b32_e32 v124, 16, v24
	v_and_b32_e32 v125, 0xffff0000, v24
	v_lshlrev_b32_e32 v126, 16, v25
	v_and_b32_e32 v127, 0xffff0000, v25
	v_lshlrev_b32_e32 v128, 16, v26
	v_and_b32_e32 v129, 0xffff0000, v26
	v_lshlrev_b32_e32 v130, 16, v27
	v_and_b32_e32 v131, 0xffff0000, v27
	v_lshlrev_b32_e32 v132, 16, v28
	v_and_b32_e32 v133, 0xffff0000, v28
	v_lshlrev_b32_e32 v134, 16, v29
	v_and_b32_e32 v135, 0xffff0000, v29
	v_lshlrev_b32_e32 v136, 16, v30
	v_and_b32_e32 v137, 0xffff0000, v30
	v_lshlrev_b32_e32 v138, 16, v31
	v_and_b32_e32 v139, 0xffff0000, v31
	v_mul_f32_e32 v59, v124, v124
	v_mul_f32_e32 v58, v125, v125
	v_fmac_f32_e32 v59, v126, v126
	v_fmac_f32_e32 v58, v127, v127
	v_fmac_f32_e32 v59, v128, v128
	v_fmac_f32_e32 v58, v129, v129
	v_fmac_f32_e32 v59, v130, v130
	v_fmac_f32_e32 v58, v131, v131
	v_fmac_f32_e32 v59, v132, v132
	v_fmac_f32_e32 v58, v133, v133
	v_fmac_f32_e32 v59, v134, v134
	v_fmac_f32_e32 v58, v135, v135
	v_fmac_f32_e32 v59, v136, v136
	v_fmac_f32_e32 v58, v137, v137
	v_fmac_f32_e32 v59, v138, v138
	v_fmac_f32_e32 v58, v139, v139
	v_add_f32_e32 v59, v59, v58
	s_nop 1
	v_add_f32_dpp v59, v59, v59 quad_perm:[1,0,3,2] row_mask:0xf bank_mask:0xf
	s_nop 1
	v_add_f32_dpp v59, v59, v59 quad_perm:[2,3,0,1] row_mask:0xf bank_mask:0xf
	s_nop 1
	v_add_f32_dpp v59, v59, v59 row_half_mirror row_mask:0xf bank_mask:0xf
	s_nop 1
	v_add_f32_dpp v59, v59, v59 row_ror:8 row_mask:0xf bank_mask:0xf
	ds_bpermute_b32 v58, v42, v59
	s_waitcnt lgkmcnt(0)
	v_add_f32_e32 v59, v59, v58
	ds_bpermute_b32 v58, v43, v59
	s_waitcnt lgkmcnt(0)
	v_add_f32_e32 v59, v59, v58
	v_fmamk_f32 v59, v59, 0x3a800000, v221
	v_rsq_f32_e32 v59, v59
	s_nop 0
	v_mul_f32_e32 v124, v59, v124
	v_fma_f32 v92, v124, v60, v92
	v_mul_f32_e32 v125, v59, v125
	v_fma_f32 v93, v125, v61, v93
	v_mul_f32_e32 v126, v59, v126
	v_fma_f32 v94, v126, v62, v94
	v_mul_f32_e32 v127, v59, v127
	v_fma_f32 v95, v127, v63, v95
	v_mul_f32_e32 v128, v59, v128
	v_fma_f32 v96, v128, v64, v96
	v_mul_f32_e32 v129, v59, v129
	v_fma_f32 v97, v129, v65, v97
	v_mul_f32_e32 v130, v59, v130
	v_fma_f32 v98, v130, v66, v98
	v_mul_f32_e32 v131, v59, v131
	v_fma_f32 v99, v131, v67, v99
	v_mul_f32_e32 v132, v59, v132
	v_fma_f32 v100, v132, v68, v100
	v_mul_f32_e32 v133, v59, v133
	v_fma_f32 v101, v133, v69, v101
	v_mul_f32_e32 v134, v59, v134
	v_fma_f32 v102, v134, v70, v102
	v_mul_f32_e32 v135, v59, v135
	v_fma_f32 v103, v135, v71, v103
	v_mul_f32_e32 v136, v59, v136
	v_fma_f32 v104, v136, v72, v104
	v_mul_f32_e32 v137, v59, v137
	v_fma_f32 v105, v137, v73, v105
	v_mul_f32_e32 v138, v59, v138
	v_fma_f32 v106, v138, v74, v106
	v_mul_f32_e32 v139, v59, v139
	v_fma_f32 v107, v139, v75, v107
	s_cmp_lg_u32 s14, 0
	s_cbranch_scc1 .Lpost_cB_done
	v_mul_f32_e32 v59, v92, v92
	v_mul_f32_e32 v58, v93, v93
	v_fmac_f32_e32 v59, v94, v94
	v_fmac_f32_e32 v58, v95, v95
	v_fmac_f32_e32 v59, v96, v96
	v_fmac_f32_e32 v58, v97, v97
	v_fmac_f32_e32 v59, v98, v98
	v_fmac_f32_e32 v58, v99, v99
	v_fmac_f32_e32 v59, v100, v100
	v_fmac_f32_e32 v58, v101, v101
	v_fmac_f32_e32 v59, v102, v102
	v_fmac_f32_e32 v58, v103, v103
	v_fmac_f32_e32 v59, v104, v104
	v_fmac_f32_e32 v58, v105, v105
	v_fmac_f32_e32 v59, v106, v106
	v_fmac_f32_e32 v58, v107, v107
	v_add_f32_e32 v59, v59, v58
	s_nop 1
	v_add_f32_dpp v59, v59, v59 quad_perm:[1,0,3,2] row_mask:0xf bank_mask:0xf
	s_nop 1
	v_add_f32_dpp v59, v59, v59 quad_perm:[2,3,0,1] row_mask:0xf bank_mask:0xf
	s_nop 1
	v_add_f32_dpp v59, v59, v59 row_half_mirror row_mask:0xf bank_mask:0xf
	s_nop 1
	v_add_f32_dpp v59, v59, v59 row_ror:8 row_mask:0xf bank_mask:0xf
	ds_bpermute_b32 v58, v42, v59
	s_waitcnt lgkmcnt(0)
	v_add_f32_e32 v59, v59, v58
	ds_bpermute_b32 v58, v43, v59
	s_waitcnt lgkmcnt(0)
	v_add_f32_e32 v59, v59, v58
	v_fmamk_f32 v59, v59, 0x3a800000, v221
	v_rsq_f32_e32 v59, v59
	s_nop 0
	v_mul_f32_e32 v124, v92, v59
	v_mul_f32_e32 v124, v76, v124
	v_mul_f32_e32 v125, v93, v59
	v_mul_f32_e32 v125, v77, v125
	v_mul_f32_e32 v126, v94, v59
	v_mul_f32_e32 v126, v78, v126
	v_mul_f32_e32 v127, v95, v59
	v_mul_f32_e32 v127, v79, v127
	v_mul_f32_e32 v128, v96, v59
	v_mul_f32_e32 v128, v80, v128
	v_mul_f32_e32 v129, v97, v59
	v_mul_f32_e32 v129, v81, v129
	v_mul_f32_e32 v130, v98, v59
	v_mul_f32_e32 v130, v82, v130
	v_mul_f32_e32 v131, v99, v59
	v_mul_f32_e32 v131, v83, v131
	v_mul_f32_e32 v132, v100, v59
	v_mul_f32_e32 v132, v84, v132
	v_mul_f32_e32 v133, v101, v59
	v_mul_f32_e32 v133, v85, v133
	v_mul_f32_e32 v134, v102, v59
	v_mul_f32_e32 v134, v86, v134
	v_mul_f32_e32 v135, v103, v59
	v_mul_f32_e32 v135, v87, v135
	v_mul_f32_e32 v136, v104, v59
	v_mul_f32_e32 v136, v88, v136
	v_mul_f32_e32 v137, v105, v59
	v_mul_f32_e32 v137, v89, v137
	v_mul_f32_e32 v138, v106, v59
	v_mul_f32_e32 v138, v90, v138
	v_mul_f32_e32 v139, v107, v59
	v_mul_f32_e32 v139, v91, v139
	v_cvt_pk_bf16_f32 v24, v124, v125
	v_cvt_pk_bf16_f32 v25, v126, v127
	v_cvt_pk_bf16_f32 v26, v128, v129
	v_cvt_pk_bf16_f32 v27, v130, v131
	v_cvt_pk_bf16_f32 v28, v132, v133
	v_cvt_pk_bf16_f32 v29, v134, v135
	v_cvt_pk_bf16_f32 v30, v136, v137
	v_cvt_pk_bf16_f32 v31, v138, v139
.Lpost_cB_done:
.Lpost_noCB:
	s_cmp_eq_u32 s72, 0
	s_cbranch_scc1 .Lpost_zA
	global_store_dwordx4 v40, v[8:11], s[76:77] offset:0
	global_store_dwordx4 v40, v[12:15], s[76:77] offset:1024
	global_store_dwordx4 v40, v[16:19], s[76:77] offset:2048
	global_store_dwordx4 v40, v[20:23], s[76:77] offset:3072
	s_cmp_lg_u32 s14, 0
	s_cbranch_scc1 .Lpost_sA_done
	global_store_dwordx2 v44, v[0:1], s[58:59]
	global_store_dwordx2 v45, v[2:3], s[58:59]
	global_store_dwordx2 v46, v[4:5], s[58:59]
	global_store_dwordx2 v47, v[6:7], s[58:59]
.Lpost_sA_done:
	s_branch .Lpost_stB
.Lpost_zA:
	s_cmp_lg_u32 s14, 0
	s_cbranch_scc1 .Lpost_stB
	global_store_dwordx2 v44, v[52:53], s[58:59]
	global_store_dwordx2 v45, v[52:53], s[58:59]
	global_store_dwordx2 v46, v[52:53], s[58:59]
	global_store_dwordx2 v47, v[52:53], s[58:59]
.Lpost_stB:
	s_cmp_eq_u32 s73, 0
	s_cbranch_scc1 .Lpost_zB
	global_store_dwordx4 v40, v[92:95], s[80:81] offset:0
	global_store_dwordx4 v40, v[96:99], s[80:81] offset:1024
	global_store_dwordx4 v40, v[100:103], s[80:81] offset:2048
	global_store_dwordx4 v40, v[104:107], s[80:81] offset:3072
	s_cmp_lg_u32 s14, 0
	s_cbranch_scc1 .Lpost_sB_done
	global_store_dwordx2 v48, v[24:25], s[58:59]
	global_store_dwordx2 v49, v[26:27], s[58:59]
	global_store_dwordx2 v50, v[28:29], s[58:59]
	global_store_dwordx2 v51, v[30:31], s[58:59]

.Lpost_zB:
	s_cmp_lg_u32 s14, 0
	s_cbranch_scc1 .Lpost_next
	s_cmp_eq_u32 s82, 0
	s_cbranch_scc1 .Lpost_next
	global_store_dwordx2 v48, v[52:53], s[58:59]
	global_store_dwordx2 v49, v[52:53], s[58:59]
	global_store_dwordx2 v50, v[52:53], s[58:59]
	global_store_dwordx2 v51, v[52:53], s[58:59]
.Lpost_next:
	s_add_u32 s0, s1, s33
	s_cmp_lt_u32 s0, 33280
	s_cbranch_scc1 .Lpost_loop
